# grid barrier: followers skip their L1 invalidate after phases whose successor reads nothing the CU touched that another CU wrote (sites 1,4,6,8,10)
# speedup vs baseline: 1.0109x; 1.0033x over previous
.Lxbar_follow:
	s_movk_i32 s99, 0x552
	s_bitcmp1_b32 s99, s98
	s_cbranch_scc1 .Lxbar_noinv
	buffer_inv sc1
.Lxbar_noinv:
	s_mov_b32 s99, 0
